# k15 + attention key loops: second key tile's K-fragment LDS reads issued with the first tile's (spare VGPRs), latency hidden under the first MFMA chain
# speedup vs baseline: 1.0056x; 1.0037x over previous
; #define LAS __attribute__((address_space(3)))
; __device__ __forceinline__ unsigned cvtpk_s(float lo, float hi) { f32x2_t v = {lo, hi}; bf16x2_t b = __builtin_convertvector(v, bf16x2_t); return __builtin_bit_cast(unsigned, b); }
; #define MFMA16(a, b, c) __builtin_amdgcn_mfma_f32_16x16x32_bf16((a), (b), (c), 0, 0, 0)
; template <int PASS>
; __device__ __forceinline__ void attn_pass(const Frame& F, const bf16_t* QKVA, bf16_t* OACC, float* LACC, bf16_t* Hout, float nb2) {
;     ...
;         for (int ks = 0; ks < 5; ++ks) {
;             u32x4 pw;
; #pragma unroll
;             for (int half = 0; half < 2; ++half) {
;                 const int kt = w + 2 * ks + half; const int ktc = kt < 16 ? kt : 15;
;                 if (ks == 4 && half == 1) { pw.z = 0u; pw.w = 0u; continue; }
;                 f32x4 sv = (f32x4){0.f, 0.f, 0.f, 0.f};
; #pragma unroll
;                 for (int kk = 0; kk < 4; ++kk) { const bf16x8 a = *(const LAS bf16x8*)(Kl + (16 * ktc + c) * KST + (8 * g + 32 * kk) * 2); sv = MFMA16(a, qf[kk], sv); }
;                 float pj[4];
; #pragma unroll
;                 for (int j = 0; j < 4; ++j) { const int kj = 16 * kt + 4 * g + j; const bool valid = (kj >= qi) && (kj <= qi + 128) && (n > 0 || kj >= 128);
;                     pj[j] = valid ? __builtin_amdgcn_exp2f(sv[j] * SCL + nb2) : 0.f; lsum += pj[j]; }
;                 if (half == 0) { pw.x = cvtpk_s(pj[0], pj[1]); pw.y = cvtpk_s(pj[2], pj[3]); } else { pw.z = cvtpk_s(pj[0], pj[1]); pw.w = cvtpk_s(pj[2], pj[3]); }
;             }
.LBB0_480:
	s_min_i32 s4, s43, 15
	v_lshl_or_b32 v128, s4, 4, v135
	v_mad_u64_u32 v[128:129], s[4:5], v128, s28, v[150:151]
	ds_read_b128 v[180:183], v128
	ds_read_b128 v[184:187], v128 offset:64
	ds_read_b128 v[188:191], v128 offset:128
	ds_read_b128 v[192:195], v128 offset:192
	s_add_i32 s4, s43, 1
	s_min_i32 s4, s4, 15
	v_lshl_or_b32 v244, s4, 4, v135
	v_mad_u64_u32 v[246:247], s[4:5], v244, s28, v[150:151]
	ds_read_b128 v[228:231], v246
	ds_read_b128 v[232:235], v246 offset:64
	ds_read_b128 v[236:239], v246 offset:128
	ds_read_b128 v[240:243], v246 offset:192
	s_waitcnt lgkmcnt(7)
	v_mfma_f32_16x16x32_bf16 v[180:183], v[180:183], v[28:31], 0
	v_add_u32_e32 v130, s42, v164
	v_add_u32_e32 v128, 1, v130
	v_cmp_lt_i32_e64 s[12:13], v128, v158
	s_waitcnt lgkmcnt(6)
	v_mfma_f32_16x16x32_bf16 v[180:183], v[184:187], v[24:27], v[180:183]
	v_cmp_lt_i32_e32 vcc, v130, v158
	v_cmp_gt_i32_e64 s[4:5], v130, v159
	v_cmp_lt_i32_e64 s[6:7], s38, v130
	s_waitcnt lgkmcnt(5)
	v_mfma_f32_16x16x32_bf16 v[180:183], v[188:191], v[20:23], v[180:183]
	v_cmp_lt_i32_e64 s[10:11], s39, v130
	v_add_u32_e32 v129, 2, v130
	s_or_b64 s[6:7], s[24:25], s[6:7]
	s_waitcnt lgkmcnt(4)
	v_mfma_f32_16x16x32_bf16 v[180:183], v[192:195], v[16:19], v[180:183]
	s_or_b64 s[34:35], vcc, s[4:5]
	s_or_b64 vcc, s[24:25], s[10:11]
	v_cmp_ge_i32_e64 s[8:9], v130, v159
	v_cmp_lt_i32_e64 s[14:15], v129, v158
	v_cmp_lt_i32_e64 s[4:5], s38, v129
	s_nop 2
	v_fmamk_f32 v128, v180, 0x3e0293ee, v208
	v_fmamk_f32 v131, v181, 0x3e0293ee, v208
	v_exp_f32_e32 v128, v128
	v_exp_f32_e32 v131, v131
	v_fmamk_f32 v180, v182, 0x3e0293ee, v208
	v_exp_f32_e32 v180, v180
	v_fmamk_f32 v181, v183, 0x3e0293ee, v208
	v_exp_f32_e32 v181, v181
	v_cndmask_b32_e64 v128, 0, v128, s[6:7]
	v_cndmask_b32_e32 v131, 0, v131, vcc
	v_cmp_gt_i32_e32 vcc, v129, v159
	v_add_u32_e32 v129, 3, v130
	s_or_b64 s[8:9], s[12:13], s[8:9]
	s_or_b64 s[4:5], s[24:25], s[4:5]
	v_cmp_lt_i32_e64 s[6:7], s38, v129
	v_cndmask_b32_e64 v128, v128, 0, s[34:35]
	v_cndmask_b32_e64 v180, 0, v180, s[4:5]
	s_or_b64 s[10:11], s[14:15], vcc
	v_cmp_lt_i32_e32 vcc, v129, v158
	v_cmp_gt_i32_e64 s[4:5], v129, v159
	s_or_b64 s[6:7], s[24:25], s[6:7]
	v_add_f32_e32 v179, v179, v128
	v_cndmask_b32_e64 v129, v131, 0, s[8:9]
	v_cndmask_b32_e64 v181, 0, v181, s[6:7]
	s_or_b64 s[4:5], vcc, s[4:5]
	v_add_f32_e32 v131, v129, v179
	v_cndmask_b32_e64 v180, v180, 0, s[10:11]
	v_add_f32_e32 v131, v180, v131
	v_cndmask_b32_e64 v181, v181, 0, s[4:5]
	s_cmpk_lg_i32 s42, 0x80
	v_add_f32_e32 v182, v181, v131
	s_mov_b64 s[4:5], -1
	s_cbranch_scc0 .LBB0_482
	s_waitcnt lgkmcnt(3)
	v_mfma_f32_16x16x32_bf16 v[184:187], v[228:231], v[28:31], 0
	v_add_u32_e32 v131, 16, v130
	v_add_u32_e32 v179, 17, v130
	v_cmp_lt_i32_e32 vcc, v131, v158
	s_waitcnt lgkmcnt(2)
	v_mfma_f32_16x16x32_bf16 v[184:187], v[232:235], v[24:27], v[184:187]
	v_cmp_gt_i32_e64 s[4:5], v131, v159
	v_cmp_lt_i32_e64 s[6:7], s38, v131
	v_cmp_ge_i32_e64 s[10:11], v131, v159
	s_waitcnt lgkmcnt(1)
	v_mfma_f32_16x16x32_bf16 v[184:187], v[236:239], v[20:23], v[184:187]
	v_cmp_lt_i32_e64 s[12:13], s39, v131
	v_cmp_lt_i32_e64 s[8:9], v179, v158
	s_or_b64 s[6:7], s[24:25], s[6:7]
	s_waitcnt lgkmcnt(0)
	v_mfma_f32_16x16x32_bf16 v[184:187], v[240:243], v[16:19], v[184:187]
	s_or_b64 s[4:5], vcc, s[4:5]
	v_add_u32_e32 v183, 18, v130
	v_cmp_lt_i32_e64 s[14:15], v183, v158
	v_cmp_gt_i32_e32 vcc, v183, v159
	v_add_u32_e32 v130, 19, v130
	s_nop 2
	v_fmamk_f32 v131, v184, 0x3e0293ee, v208
	v_fmamk_f32 v179, v185, 0x3e0293ee, v208
	v_exp_f32_e32 v131, v131
	v_exp_f32_e32 v179, v179
	v_fmamk_f32 v184, v186, 0x3e0293ee, v208
	v_exp_f32_e32 v184, v184
	v_cndmask_b32_e64 v131, 0, v131, s[6:7]
	s_or_b64 s[6:7], s[24:25], s[12:13]
	v_cndmask_b32_e64 v179, 0, v179, s[6:7]
	v_cndmask_b32_e64 v131, v131, 0, s[4:5]
	s_or_b64 s[4:5], s[8:9], s[10:11]
	v_cndmask_b32_e64 v185, v179, 0, s[4:5]
	v_cmp_lt_i32_e64 s[4:5], s38, v183
	s_or_b64 s[4:5], s[24:25], s[4:5]
	v_cmp_lt_i32_e64 s[6:7], s38, v130
	v_cndmask_b32_e64 v183, 0, v184, s[4:5]
	v_fmamk_f32 v184, v187, 0x3e0293ee, v208
	v_exp_f32_e32 v184, v184
	s_or_b64 s[4:5], s[14:15], vcc
	v_add_f32_e32 v179, v182, v131
	v_cndmask_b32_e64 v183, v183, 0, s[4:5]
	v_cmp_lt_i32_e32 vcc, v130, v158
	v_cmp_gt_i32_e64 s[4:5], v130, v159
	s_or_b64 s[6:7], s[24:25], s[6:7]
	v_add_f32_e32 v179, v185, v179
	v_cndmask_b32_e64 v130, 0, v184, s[6:7]
	s_or_b64 s[4:5], vcc, s[4:5]
	v_add_f32_e32 v179, v183, v179
	v_cndmask_b32_e64 v184, v130, 0, s[4:5]
	v_add_f32_e32 v179, v184, v179
	v_cvt_pk_bf16_f32 v130, v131, v185
	v_cvt_pk_bf16_f32 v131, v183, v184
	s_mov_b64 s[4:5], 0

; #define LAS __attribute__((address_space(3)))
; __device__ __forceinline__ unsigned cvtpk_s(float lo, float hi) { f32x2_t v = {lo, hi}; bf16x2_t b = __builtin_convertvector(v, bf16x2_t); return __builtin_bit_cast(unsigned, b); }
; #define MFMA16(a, b, c) __builtin_amdgcn_mfma_f32_16x16x32_bf16((a), (b), (c), 0, 0, 0)
; template <int PASS>
; __device__ __forceinline__ void attn_pass(const Frame& F, const bf16_t* QKVA, bf16_t* OACC, float* LACC, bf16_t* Hout, float nb2) {
;     ...
;         for (int ks = 0; ks < 5; ++ks) {
;             u32x4 pw;
; #pragma unroll
;             for (int half = 0; half < 2; ++half) {
;                 const int kt = w + 2 * ks + half; const int ktc = kt < 16 ? kt : 15;
;                 if (ks == 4 && half == 1) { pw.z = 0u; pw.w = 0u; continue; }
;                 f32x4 sv = (f32x4){0.f, 0.f, 0.f, 0.f};
; #pragma unroll
;                 for (int kk = 0; kk < 4; ++kk) { const bf16x8 a = *(const LAS bf16x8*)(Kl + (16 * ktc + c) * KST + (8 * g + 32 * kk) * 2); sv = MFMA16(a, qf[kk], sv); }
;                 float pj[4];
; #pragma unroll
;                 for (int j = 0; j < 4; ++j) { const int kj = 16 * kt + 4 * g + j; const bool valid = (kj >= qi) && (kj <= qi + 128) && (n > 0 || kj >= 128);
;                     pj[j] = valid ? __builtin_amdgcn_exp2f(sv[j] * SCL + nb2) : 0.f; lsum += pj[j]; }
;                 if (half == 0) { pw.x = cvtpk_s(pj[0], pj[1]); pw.y = cvtpk_s(pj[2], pj[3]); } else { pw.z = cvtpk_s(pj[0], pj[1]); pw.w = cvtpk_s(pj[2], pj[3]); }
;             }
.LBB0_552:
	s_min_i32 s6, s42, 15
	v_lshl_or_b32 v128, s6, 4, v135
	v_mad_u64_u32 v[130:131], s[6:7], v128, s28, v[150:151]
	ds_read_b128 v[184:187], v130
	ds_read_b128 v[188:191], v130 offset:64
	ds_read_b128 v[192:195], v130 offset:128
	ds_read_b128 v[196:199], v130 offset:192
	s_add_i32 s6, s42, 1
	s_min_i32 s6, s6, 15
	v_lshl_or_b32 v244, s6, 4, v135
	v_mad_u64_u32 v[246:247], s[6:7], v244, s28, v[150:151]
	ds_read_b128 v[228:231], v246
	ds_read_b128 v[232:235], v246 offset:64
	ds_read_b128 v[236:239], v246 offset:128
	ds_read_b128 v[240:243], v246 offset:192
	s_waitcnt lgkmcnt(7)
	v_mfma_f32_16x16x32_bf16 v[184:187], v[184:187], v[16:19], 0
	v_add_u32_e32 v128, s20, v170
	v_add_u32_e32 v129, 1, v128
	v_cmp_lt_i32_e64 s[14:15], v129, v164
	s_waitcnt lgkmcnt(6)
	v_mfma_f32_16x16x32_bf16 v[184:187], v[188:191], v[12:15], v[184:187]
	v_cmp_lt_i32_e32 vcc, v128, v164
	v_cmp_gt_i32_e64 s[6:7], v128, v165
	v_add_u32_e32 v130, 2, v128
	s_waitcnt lgkmcnt(5)
	v_mfma_f32_16x16x32_bf16 v[184:187], v[192:195], v[8:11], v[184:187]
	v_cmp_lt_i32_e64 s[8:9], s38, v128
	v_cmp_lt_i32_e64 s[12:13], s39, v128
	s_or_b64 s[34:35], vcc, s[6:7]
	s_waitcnt lgkmcnt(4)
	v_mfma_f32_16x16x32_bf16 v[184:187], v[196:199], v[4:7], v[184:187]
	v_cmp_lt_i32_e64 s[6:7], s38, v130
	s_or_b64 s[8:9], s[24:25], s[8:9]
	s_or_b64 vcc, s[24:25], s[12:13]
	s_or_b64 s[6:7], s[24:25], s[6:7]
	v_cmp_ge_i32_e64 s[10:11], v128, v165
	s_nop 2
	v_fmamk_f32 v129, v184, 0x3e0293ee, v208
	v_fmamk_f32 v131, v185, 0x3e0293ee, v208
	v_fmamk_f32 v184, v186, 0x3e0293ee, v208
	v_exp_f32_e32 v129, v129
	v_exp_f32_e32 v131, v131
	v_exp_f32_e32 v184, v184
	v_fmamk_f32 v185, v187, 0x3e0293ee, v208
	v_exp_f32_e32 v185, v185
	v_cmp_lt_i32_e64 s[16:17], v130, v164
	v_cndmask_b32_e64 v129, 0, v129, s[8:9]
	v_cndmask_b32_e32 v131, 0, v131, vcc
	v_cmp_gt_i32_e32 vcc, v130, v165
	v_cndmask_b32_e64 v130, 0, v184, s[6:7]
	v_add_u32_e32 v184, 3, v128
	s_or_b64 s[10:11], s[14:15], s[10:11]
	v_cmp_lt_i32_e64 s[8:9], s38, v184
	v_cndmask_b32_e64 v129, v129, 0, s[34:35]
	s_or_b64 s[12:13], s[16:17], vcc
	v_cmp_lt_i32_e32 vcc, v184, v164
	v_cmp_gt_i32_e64 s[6:7], v184, v165
	s_or_b64 s[8:9], s[24:25], s[8:9]
	v_add_f32_e32 v155, v155, v129
	v_cndmask_b32_e64 v184, v131, 0, s[10:11]
	v_cndmask_b32_e64 v186, 0, v185, s[8:9]
	s_or_b64 s[6:7], vcc, s[6:7]
	v_add_f32_e32 v131, v184, v155
	v_cndmask_b32_e64 v185, v130, 0, s[12:13]
	v_add_f32_e32 v130, v185, v131
	v_cndmask_b32_e64 v186, v186, 0, s[6:7]
	s_cmpk_lg_i32 s20, 0x80
	v_add_f32_e32 v187, v186, v130
	s_mov_b64 s[6:7], -1
	s_cbranch_scc0 .LBB0_554
	s_waitcnt lgkmcnt(3)
	v_mfma_f32_16x16x32_bf16 v[188:191], v[228:231], v[16:19], 0
	v_add_u32_e32 v131, 16, v128
	v_cmp_lt_i32_e32 vcc, v131, v164
	v_cmp_gt_i32_e64 s[6:7], v131, v165
	s_waitcnt lgkmcnt(2)
	v_mfma_f32_16x16x32_bf16 v[188:191], v[232:235], v[12:15], v[188:191]
	v_cmp_lt_i32_e64 s[8:9], s38, v131
	v_cmp_ge_i32_e64 s[12:13], v131, v165
	v_cmp_lt_i32_e64 s[14:15], s39, v131
	s_waitcnt lgkmcnt(1)
	v_mfma_f32_16x16x32_bf16 v[188:191], v[236:239], v[8:11], v[188:191]
	v_add_u32_e32 v155, 17, v128
	v_cmp_lt_i32_e64 s[10:11], v155, v164
	s_or_b64 s[8:9], s[24:25], s[8:9]
	s_waitcnt lgkmcnt(0)
	v_mfma_f32_16x16x32_bf16 v[188:191], v[240:243], v[4:7], v[188:191]
	s_or_b64 s[6:7], vcc, s[6:7]
	v_add_u32_e32 v209, 18, v128
	v_cmp_lt_i32_e64 s[16:17], v209, v164
	v_cmp_gt_i32_e32 vcc, v209, v165
	v_add_u32_e32 v128, 19, v128
	s_nop 2
	v_fmamk_f32 v130, v188, 0x3e0293ee, v208
	v_fmamk_f32 v131, v189, 0x3e0293ee, v208
	v_exp_f32_e32 v130, v130
	v_exp_f32_e32 v131, v131
	v_fmamk_f32 v155, v190, 0x3e0293ee, v208
	v_exp_f32_e32 v155, v155
	v_cndmask_b32_e64 v130, 0, v130, s[8:9]
	s_or_b64 s[8:9], s[24:25], s[14:15]
	v_cndmask_b32_e64 v131, 0, v131, s[8:9]
	v_cndmask_b32_e64 v130, v130, 0, s[6:7]
	s_or_b64 s[6:7], s[10:11], s[12:13]
	v_cndmask_b32_e64 v131, v131, 0, s[6:7]
	v_cmp_lt_i32_e64 s[6:7], s38, v209
	s_or_b64 s[6:7], s[24:25], s[6:7]
	v_add_f32_e32 v188, v187, v130
	v_cndmask_b32_e64 v155, 0, v155, s[6:7]
	s_or_b64 s[6:7], s[16:17], vcc
	v_add_f32_e32 v188, v131, v188
	v_cndmask_b32_e64 v189, v155, 0, s[6:7]
	v_add_f32_e32 v155, v189, v188
	v_fmamk_f32 v188, v191, 0x3e0293ee, v208
	v_exp_f32_e32 v188, v188
	v_cmp_lt_i32_e64 s[8:9], s38, v128
	v_cmp_lt_i32_e32 vcc, v128, v164
	v_cmp_gt_i32_e64 s[6:7], v128, v165
	s_or_b64 s[8:9], s[24:25], s[8:9]
	v_cndmask_b32_e64 v128, 0, v188, s[8:9]
	s_or_b64 s[6:7], vcc, s[6:7]
	v_cndmask_b32_e64 v128, v128, 0, s[6:7]
	v_add_f32_e32 v155, v128, v155
	v_cvt_pk_bf16_f32 v130, v130, v131
	v_cvt_pk_bf16_f32 v131, v189, v128
	s_mov_b64 s[6:7], 0

; #define LAS __attribute__((address_space(3)))
; __device__ __forceinline__ unsigned cvtpk_s(float lo, float hi) { f32x2_t v = {lo, hi}; bf16x2_t b = __builtin_convertvector(v, bf16x2_t); return __builtin_bit_cast(unsigned, b); }
; #define MFMA16(a, b, c) __builtin_amdgcn_mfma_f32_16x16x32_bf16((a), (b), (c), 0, 0, 0)
; template <int PASS>
; __device__ __forceinline__ void attn_pass(const Frame& F, const bf16_t* QKVA, bf16_t* OACC, float* LACC, bf16_t* Hout, float nb2) {
;     ...
;         for (int ks = 0; ks < 5; ++ks) {
;             u32x4 pw;
; #pragma unroll
;             for (int half = 0; half < 2; ++half) {
;                 const int kt = w + 2 * ks + half; const int ktc = kt < 16 ? kt : 15;
;                 if (ks == 4 && half == 1) { pw.z = 0u; pw.w = 0u; continue; }
;                 f32x4 sv = (f32x4){0.f, 0.f, 0.f, 0.f};
; #pragma unroll
;                 for (int kk = 0; kk < 4; ++kk) { const bf16x8 a = *(const LAS bf16x8*)(Kl + (16 * ktc + c) * KST + (8 * g + 32 * kk) * 2); sv = MFMA16(a, qf[kk], sv); }
;                 float pj[4];
; #pragma unroll
;                 for (int j = 0; j < 4; ++j) { const int kj = 16 * kt + 4 * g + j; const bool valid = (kj >= qi) && (kj <= qi + 128) && (n > 0 || kj >= 128);
;                     pj[j] = valid ? __builtin_amdgcn_exp2f(sv[j] * SCL + nb2) : 0.f; lsum += pj[j]; }
;                 if (half == 0) { pw.x = cvtpk_s(pj[0], pj[1]); pw.y = cvtpk_s(pj[2], pj[3]); } else { pw.z = cvtpk_s(pj[0], pj[1]); pw.w = cvtpk_s(pj[2], pj[3]); }
;             }
.LBB0_634:
	s_min_i32 s4, s36, 15
	v_lshl_or_b32 v128, s4, 4, v143
	v_mad_u64_u32 v[130:131], s[4:5], v128, s24, v[148:149]
	ds_read_b128 v[178:181], v130
	ds_read_b128 v[182:185], v130 offset:64
	ds_read_b128 v[186:189], v130 offset:128
	ds_read_b128 v[190:193], v130 offset:192
	s_add_i32 s4, s36, 1
	s_min_i32 s4, s4, 15
	v_lshl_or_b32 v244, s4, 4, v143
	v_mad_u64_u32 v[246:247], s[4:5], v244, s24, v[148:149]
	ds_read_b128 v[228:231], v246
	ds_read_b128 v[232:235], v246 offset:64
	ds_read_b128 v[236:239], v246 offset:128
	ds_read_b128 v[240:243], v246 offset:192
	s_waitcnt lgkmcnt(7)
	v_mfma_f32_16x16x32_bf16 v[178:181], v[178:181], v[28:31], 0
	v_add_u32_e32 v128, s29, v164
	v_add_u32_e32 v129, 1, v128
	v_cmp_lt_i32_e64 s[12:13], v129, v158
	s_waitcnt lgkmcnt(6)
	v_mfma_f32_16x16x32_bf16 v[178:181], v[182:185], v[24:27], v[178:181]
	v_cmp_lt_i32_e32 vcc, v128, v158
	v_cmp_gt_i32_e64 s[4:5], v128, v159
	v_add_u32_e32 v130, 2, v128
	s_waitcnt lgkmcnt(5)
	v_mfma_f32_16x16x32_bf16 v[178:181], v[186:189], v[20:23], v[178:181]
	v_cmp_lt_i32_e64 s[6:7], s26, v128
	v_cmp_lt_i32_e64 s[10:11], s27, v128
	s_or_b64 s[34:35], vcc, s[4:5]
	s_waitcnt lgkmcnt(4)
	v_mfma_f32_16x16x32_bf16 v[178:181], v[190:193], v[16:19], v[178:181]
	v_cmp_lt_i32_e64 s[4:5], s26, v130
	s_or_b64 s[6:7], s[20:21], s[6:7]
	s_or_b64 vcc, s[20:21], s[10:11]
	s_or_b64 s[4:5], s[20:21], s[4:5]
	v_cmp_ge_i32_e64 s[8:9], v128, v159
	s_nop 2
	v_fmamk_f32 v129, v178, 0x3e0293ee, v208
	v_fmamk_f32 v131, v179, 0x3e0293ee, v208
	v_fmamk_f32 v178, v180, 0x3e0293ee, v208
	v_exp_f32_e32 v129, v129
	v_exp_f32_e32 v131, v131
	v_exp_f32_e32 v178, v178
	v_fmamk_f32 v179, v181, 0x3e0293ee, v208
	v_exp_f32_e32 v179, v179
	v_cmp_lt_i32_e64 s[14:15], v130, v158
	v_cndmask_b32_e64 v129, 0, v129, s[6:7]
	v_cndmask_b32_e32 v131, 0, v131, vcc
	v_cmp_gt_i32_e32 vcc, v130, v159
	v_cndmask_b32_e64 v130, 0, v178, s[4:5]
	v_add_u32_e32 v178, 3, v128
	s_or_b64 s[8:9], s[12:13], s[8:9]
	v_cmp_lt_i32_e64 s[6:7], s26, v178
	v_cndmask_b32_e64 v129, v129, 0, s[34:35]
	s_or_b64 s[10:11], s[14:15], vcc
	v_cmp_lt_i32_e32 vcc, v178, v158
	v_cmp_gt_i32_e64 s[4:5], v178, v159
	s_or_b64 s[6:7], s[20:21], s[6:7]
	v_add_f32_e32 v144, v144, v129
	v_cndmask_b32_e64 v178, v131, 0, s[8:9]
	v_cndmask_b32_e64 v180, 0, v179, s[6:7]
	s_or_b64 s[4:5], vcc, s[4:5]
	v_add_f32_e32 v131, v178, v144
	v_cndmask_b32_e64 v179, v130, 0, s[10:11]
	v_add_f32_e32 v130, v179, v131
	v_cndmask_b32_e64 v180, v180, 0, s[4:5]
	s_cmpk_lg_i32 s29, 0x80
	v_add_f32_e32 v181, v180, v130
	s_mov_b64 s[4:5], -1
	s_cbranch_scc0 .LBB0_636
	s_waitcnt lgkmcnt(3)
	v_mfma_f32_16x16x32_bf16 v[182:185], v[228:231], v[28:31], 0
	v_add_u32_e32 v131, 16, v128
	v_cmp_lt_i32_e32 vcc, v131, v158
	v_cmp_gt_i32_e64 s[4:5], v131, v159
	s_waitcnt lgkmcnt(2)
	v_mfma_f32_16x16x32_bf16 v[182:185], v[232:235], v[24:27], v[182:185]
	v_cmp_lt_i32_e64 s[6:7], s26, v131
	v_cmp_ge_i32_e64 s[10:11], v131, v159
	v_cmp_lt_i32_e64 s[12:13], s27, v131
	s_waitcnt lgkmcnt(1)
	v_mfma_f32_16x16x32_bf16 v[182:185], v[236:239], v[20:23], v[182:185]
	v_add_u32_e32 v144, 17, v128
	v_cmp_lt_i32_e64 s[8:9], v144, v158
	s_or_b64 s[6:7], s[20:21], s[6:7]
	s_waitcnt lgkmcnt(0)
	v_mfma_f32_16x16x32_bf16 v[182:185], v[240:243], v[16:19], v[182:185]
	s_or_b64 s[4:5], vcc, s[4:5]
	v_add_u32_e32 v198, 18, v128
	v_cmp_lt_i32_e64 s[14:15], v198, v158
	v_cmp_gt_i32_e32 vcc, v198, v159
	v_add_u32_e32 v128, 19, v128
	s_nop 2
	v_fmamk_f32 v130, v182, 0x3e0293ee, v208
	v_fmamk_f32 v131, v183, 0x3e0293ee, v208
	v_exp_f32_e32 v130, v130
	v_exp_f32_e32 v131, v131
	v_fmamk_f32 v144, v184, 0x3e0293ee, v208
	v_exp_f32_e32 v144, v144
	v_cndmask_b32_e64 v130, 0, v130, s[6:7]
	s_or_b64 s[6:7], s[20:21], s[12:13]
	v_cndmask_b32_e64 v131, 0, v131, s[6:7]
	v_cndmask_b32_e64 v130, v130, 0, s[4:5]
	s_or_b64 s[4:5], s[8:9], s[10:11]
	v_cndmask_b32_e64 v131, v131, 0, s[4:5]
	v_cmp_lt_i32_e64 s[4:5], s26, v198
	s_or_b64 s[4:5], s[20:21], s[4:5]
	v_add_f32_e32 v182, v181, v130
	v_cndmask_b32_e64 v144, 0, v144, s[4:5]
	s_or_b64 s[4:5], s[14:15], vcc
	v_add_f32_e32 v182, v131, v182
	v_cndmask_b32_e64 v183, v144, 0, s[4:5]
	v_add_f32_e32 v144, v183, v182
	v_fmamk_f32 v182, v185, 0x3e0293ee, v208
	v_exp_f32_e32 v182, v182
	v_cmp_lt_i32_e64 s[6:7], s26, v128
	v_cmp_lt_i32_e32 vcc, v128, v158
	v_cmp_gt_i32_e64 s[4:5], v128, v159
	s_or_b64 s[6:7], s[20:21], s[6:7]
	v_cndmask_b32_e64 v128, 0, v182, s[6:7]
	s_or_b64 s[4:5], vcc, s[4:5]
	v_cndmask_b32_e64 v128, v128, 0, s[4:5]
	v_add_f32_e32 v144, v128, v144
	v_cvt_pk_bf16_f32 v130, v130, v131
	v_cvt_pk_bf16_f32 v131, v183, v128
	s_mov_b64 s[4:5], 0
